# NSA compressed unit top-k selection: candidates loaded once into VGPRs, six rounds on registers (was an LDS read + wait per candidate per round)
# speedup vs baseline: 1.0083x; 1.0016x over previous
; DI unsigned pack2(float a, float b) { f32x2 v = {a, b}; bf16x2_t r = __builtin_convertvector(v, bf16x2_t); return __builtin_bit_cast(unsigned, r); }
; DI int crow(int i, int h) { return (i & 3) + 8 * (i >> 2) + 4 * h; }
; DI void store_plain(const f32x16 (&o)[2], float inv, bf16_t* op) {
;   const int h = (threadIdx.x & 63) >> 5;
; #pragma unroll
;   for (int dt = 0; dt < 2; ++dt)
; #pragma unroll
;     for (int g = 0; g < 4; ++g)
;       *(u32x2*)(op + 32 * dt + 8 * g + 4 * h) = (u32x2){pack2(o[dt][4 * g] * inv, o[dt][4 * g + 1] * inv), pack2(o[dt][4 * g + 2] * inv, o[dt][4 * g + 3] * inv)};
; }
; DI void nsa_cmp_unit(const Params& p, int u, char* smem) {
;     ...
;   __syncthreads();
;   float* imp_s = (float*)smem;
; #pragma unroll
;   for (int jt = 0; jt < 2; ++jt)
; #pragma unroll
;     for (int i = 0; i < 16; ++i) imp_s[(32 * w + r) * 65 + 32 * jt + crow(i, h)] = imp[jt][i];
;   __syncthreads();
;   if (tid < 128) {
;     const int t = 128 * qb + tid, cur = t >> 6;
;     ull mask = 1ull | (1ull << cur);
;     if (cur >= 2) {
;       const int need = (cur - 1) < 6 ? (cur - 1) : 6;
;       for (int k = 0; k < need; ++k) {
;         int best = 1; float bv = -1.f;
;         for (int jj = 1; jj < cur; ++jj) {
;           const float v = imp_s[tid * 65 + jj];
;           if (!((mask >> jj) & 1ull) && v > bv) { bv = v; best = jj; }
.LBB0_448:
	s_lshl_b32 s58, s55, 7
	v_lshl_add_u64 v[66:67], v[118:119], 0, s[58:59]
	v_cvt_pk_bf16_f32 v34, v34, v35
	v_cvt_pk_bf16_f32 v35, v36, v37
	global_store_dwordx2 v[66:67], v[34:35], off
	v_cvt_pk_bf16_f32 v34, v38, v39
	v_cvt_pk_bf16_f32 v35, v40, v41
	global_store_dwordx2 v[66:67], v[34:35], off offset:16
	v_cvt_pk_bf16_f32 v34, v42, v43
	v_cvt_pk_bf16_f32 v35, v44, v45
	global_store_dwordx2 v[66:67], v[34:35], off offset:32
	v_cvt_pk_bf16_f32 v34, v46, v47
	v_cvt_pk_bf16_f32 v35, v48, v49
	global_store_dwordx2 v[66:67], v[34:35], off offset:48
	v_cvt_pk_bf16_f32 v34, v50, v51
	v_cvt_pk_bf16_f32 v35, v52, v53
	global_store_dwordx2 v[66:67], v[34:35], off offset:64
	v_cvt_pk_bf16_f32 v34, v54, v55
	v_cvt_pk_bf16_f32 v35, v56, v57
	s_add_i32 s30, s30, 1
	global_store_dwordx2 v[66:67], v[34:35], off offset:80
	v_cvt_pk_bf16_f32 v34, v58, v59
	v_cvt_pk_bf16_f32 v35, v60, v61
	global_store_dwordx2 v[66:67], v[34:35], off offset:96
	v_cvt_pk_bf16_f32 v34, v62, v63
	v_cvt_pk_bf16_f32 v35, v64, v65
	s_cmp_eq_u32 s30, 8
	global_store_dwordx2 v[66:67], v[34:35], off offset:112
	s_cbranch_scc0 .LBB0_431
	v_or_b32_e32 v0, s29, v124
	s_movk_i32 s4, 0x104
	v_mul_lo_u32 v0, v0, s4
	s_movk_i32 s4, 0x80
	v_add3_u32 v0, 0, v0, v125
	v_cmp_gt_i32_e32 vcc, s4, v114
	s_barrier
	ds_write2_b32 v0, v18, v19 offset1:1
	ds_write2_b32 v0, v20, v21 offset0:2 offset1:3
	ds_write2_b32 v0, v22, v23 offset0:8 offset1:9
	ds_write2_b32 v0, v24, v25 offset0:10 offset1:11
	ds_write2_b32 v0, v26, v27 offset0:16 offset1:17
	ds_write2_b32 v0, v28, v29 offset0:18 offset1:19
	ds_write2_b32 v0, v30, v31 offset0:24 offset1:25
	ds_write2_b32 v0, v32, v33 offset0:26 offset1:27
	ds_write2_b32 v0, v2, v3 offset0:32 offset1:33
	ds_write2_b32 v0, v4, v5 offset0:34 offset1:35
	ds_write2_b32 v0, v6, v7 offset0:40 offset1:41
	ds_write2_b32 v0, v8, v9 offset0:42 offset1:43
	ds_write2_b32 v0, v10, v11 offset0:48 offset1:49
	ds_write2_b32 v0, v12, v13 offset0:50 offset1:51
	ds_write2_b32 v0, v14, v15 offset0:56 offset1:57
	ds_write2_b32 v0, v16, v17 offset0:58 offset1:59
	s_waitcnt lgkmcnt(0)
	s_barrier
	s_and_saveexec_b64 s[4:5], vcc
	s_cbranch_execz .LBB0_429
	v_add_u32_e32 v2, s28, v114
	v_ashrrev_i32_e32 v3, 6, v2
	v_lshlrev_b64 v[4:5], v3, 1
	v_or_b32_e32 v4, 1, v4
	v_cmp_lt_i32_e32 vcc, 1, v3
	s_and_saveexec_b64 s[8:9], vcc
	s_cbranch_execz .LBB0_428
	s_movk_i32 s6, 0x104
	v_min_u32_e32 v0, 7, v3
	v_mul_lo_u32 v7, v114, s6
	v_add_u32_e32 v6, -2, v0
	v_add3_u32 v7, 0, 4, v7
	v_readfirstlane_b32 s28, v3
	s_nop 3
	s_cmp_lt_u32 s28, 12
	s_cbranch_scc1 .Lsel_small
	ds_read_b32 v34, v7
	ds_read_b32 v35, v7 offset:4
	ds_read_b32 v36, v7 offset:8
	ds_read_b32 v37, v7 offset:12
	ds_read_b32 v38, v7 offset:16
	ds_read_b32 v39, v7 offset:20
	ds_read_b32 v40, v7 offset:24
	ds_read_b32 v41, v7 offset:28
	ds_read_b32 v42, v7 offset:32
	ds_read_b32 v43, v7 offset:36
	ds_read_b32 v44, v7 offset:40
	ds_read_b32 v45, v7 offset:44
	ds_read_b32 v46, v7 offset:48
	ds_read_b32 v47, v7 offset:52
	s_waitcnt lgkmcnt(0)
	ds_read_b32 v48, v7 offset:56
	ds_read_b32 v49, v7 offset:60
	ds_read_b32 v50, v7 offset:64
	ds_read_b32 v51, v7 offset:68
	ds_read_b32 v52, v7 offset:72
	ds_read_b32 v53, v7 offset:76
	ds_read_b32 v54, v7 offset:80
	ds_read_b32 v55, v7 offset:84
	ds_read_b32 v56, v7 offset:88
	ds_read_b32 v57, v7 offset:92
	ds_read_b32 v58, v7 offset:96
	ds_read_b32 v59, v7 offset:100
	ds_read_b32 v60, v7 offset:104
	ds_read_b32 v61, v7 offset:108
	s_waitcnt lgkmcnt(0)
	ds_read_b32 v62, v7 offset:112
	ds_read_b32 v63, v7 offset:116
	ds_read_b32 v64, v7 offset:120
	ds_read_b32 v65, v7 offset:124
	ds_read_b32 v66, v7 offset:128
	ds_read_b32 v67, v7 offset:132
	ds_read_b32 v68, v7 offset:136
	ds_read_b32 v69, v7 offset:140
	ds_read_b32 v70, v7 offset:144
	ds_read_b32 v71, v7 offset:148
	ds_read_b32 v72, v7 offset:152
	ds_read_b32 v73, v7 offset:156
	ds_read_b32 v74, v7 offset:160
	ds_read_b32 v75, v7 offset:164
	s_waitcnt lgkmcnt(0)
	ds_read_b32 v76, v7 offset:168
	ds_read_b32 v77, v7 offset:172
	ds_read_b32 v78, v7 offset:176
	ds_read_b32 v79, v7 offset:180
	ds_read_b32 v80, v7 offset:184
	ds_read_b32 v81, v7 offset:188
	ds_read_b32 v82, v7 offset:192
	ds_read_b32 v83, v7 offset:196
	ds_read_b32 v84, v7 offset:200
	ds_read_b32 v85, v7 offset:204
	ds_read_b32 v86, v7 offset:208
	ds_read_b32 v87, v7 offset:212
	ds_read_b32 v88, v7 offset:216
	ds_read_b32 v89, v7 offset:220
	s_waitcnt lgkmcnt(0)
	ds_read_b32 v90, v7 offset:224
	ds_read_b32 v91, v7 offset:228
	ds_read_b32 v92, v7 offset:232
	ds_read_b32 v93, v7 offset:236
	ds_read_b32 v94, v7 offset:240
	ds_read_b32 v95, v7 offset:244
	s_add_i32 s100, s28, -1
	s_min_u32 s100, s100, 6
	v_mov_b32_e32 v12, -1.0
	s_waitcnt lgkmcnt(0)
; DI void nsa_cmp_unit(const Params& p, int u, char* smem) {
;     ...
;       for (int k = 0; k < need; ++k) {
;         int best = 1; float bv = -1.f;
;         for (int jj = 1; jj < cur; ++jj) {
;           const float v = imp_s[tid * 65 + jj];
;           if (!((mask >> jj) & 1ull) && v > bv) { bv = v; best = jj; }
	v_cmp_gt_u32_e64 s[6:7], v3, 1
	v_cmp_gt_u32_e64 s[10:11], v3, 2
	v_cmp_gt_u32_e64 vcc, v3, 3
	v_cndmask_b32_e64 v34, v12, v34, s[6:7]
	v_cmp_gt_u32_e64 s[6:7], v3, 4
	v_cndmask_b32_e64 v35, v12, v35, s[10:11]
	v_cmp_gt_u32_e64 s[10:11], v3, 5
	v_cndmask_b32_e64 v36, v12, v36, vcc
	v_cmp_gt_u32_e64 vcc, v3, 6
	v_cndmask_b32_e64 v37, v12, v37, s[6:7]
	v_cmp_gt_u32_e64 s[6:7], v3, 7
	v_cndmask_b32_e64 v38, v12, v38, s[10:11]
	v_cmp_gt_u32_e64 s[10:11], v3, 8
	v_cndmask_b32_e64 v39, v12, v39, vcc
	v_cmp_gt_u32_e64 vcc, v3, 9
	v_cndmask_b32_e64 v40, v12, v40, s[6:7]
	v_cmp_gt_u32_e64 s[6:7], v3, 10
	v_cndmask_b32_e64 v41, v12, v41, s[10:11]
	v_cmp_gt_u32_e64 s[10:11], v3, 11
	v_cndmask_b32_e64 v42, v12, v42, vcc
	v_cmp_gt_u32_e64 vcc, v3, 12
	v_cndmask_b32_e64 v43, v12, v43, s[6:7]
	v_cmp_gt_u32_e64 s[6:7], v3, 13
	v_cndmask_b32_e64 v44, v12, v44, s[10:11]
	v_cmp_gt_u32_e64 s[10:11], v3, 14
	v_cndmask_b32_e64 v45, v12, v45, vcc
	v_cmp_gt_u32_e64 vcc, v3, 15
	v_cndmask_b32_e64 v46, v12, v46, s[6:7]
	v_cmp_gt_u32_e64 s[6:7], v3, 16
	v_cndmask_b32_e64 v47, v12, v47, s[10:11]
	v_cmp_gt_u32_e64 s[10:11], v3, 17
	v_cndmask_b32_e64 v48, v12, v48, vcc
	v_cmp_gt_u32_e64 vcc, v3, 18
	v_cndmask_b32_e64 v49, v12, v49, s[6:7]
	v_cmp_gt_u32_e64 s[6:7], v3, 19
	v_cndmask_b32_e64 v50, v12, v50, s[10:11]
	v_cmp_gt_u32_e64 s[10:11], v3, 20
	v_cndmask_b32_e64 v51, v12, v51, vcc
	v_cmp_gt_u32_e64 vcc, v3, 21
	v_cndmask_b32_e64 v52, v12, v52, s[6:7]
	v_cmp_gt_u32_e64 s[6:7], v3, 22
	v_cndmask_b32_e64 v53, v12, v53, s[10:11]
	v_cmp_gt_u32_e64 s[10:11], v3, 23
	v_cndmask_b32_e64 v54, v12, v54, vcc
	v_cmp_gt_u32_e64 vcc, v3, 24
	v_cndmask_b32_e64 v55, v12, v55, s[6:7]
	v_cmp_gt_u32_e64 s[6:7], v3, 25
	v_cndmask_b32_e64 v56, v12, v56, s[10:11]
	v_cmp_gt_u32_e64 s[10:11], v3, 26
	v_cndmask_b32_e64 v57, v12, v57, vcc
	v_cmp_gt_u32_e64 vcc, v3, 27
	v_cndmask_b32_e64 v58, v12, v58, s[6:7]
	v_cmp_gt_u32_e64 s[6:7], v3, 28
	v_cndmask_b32_e64 v59, v12, v59, s[10:11]
	v_cmp_gt_u32_e64 s[10:11], v3, 29
	v_cndmask_b32_e64 v60, v12, v60, vcc
	v_cmp_gt_u32_e64 vcc, v3, 30
	v_cndmask_b32_e64 v61, v12, v61, s[6:7]
	v_cmp_gt_u32_e64 s[6:7], v3, 31
	v_cndmask_b32_e64 v62, v12, v62, s[10:11]
	v_cmp_gt_u32_e64 s[10:11], v3, 32
	v_cndmask_b32_e64 v63, v12, v63, vcc
	v_cmp_gt_u32_e64 vcc, v3, 33
	v_cndmask_b32_e64 v64, v12, v64, s[6:7]
	v_cmp_gt_u32_e64 s[6:7], v3, 34
	v_cndmask_b32_e64 v65, v12, v65, s[10:11]
	v_cmp_gt_u32_e64 s[10:11], v3, 35
	v_cndmask_b32_e64 v66, v12, v66, vcc
	v_cmp_gt_u32_e64 vcc, v3, 36
	v_cndmask_b32_e64 v67, v12, v67, s[6:7]
	v_cmp_gt_u32_e64 s[6:7], v3, 37
	v_cndmask_b32_e64 v68, v12, v68, s[10:11]
	v_cmp_gt_u32_e64 s[10:11], v3, 38
	v_cndmask_b32_e64 v69, v12, v69, vcc
	v_cmp_gt_u32_e64 vcc, v3, 39
	v_cndmask_b32_e64 v70, v12, v70, s[6:7]
	v_cmp_gt_u32_e64 s[6:7], v3, 40
	v_cndmask_b32_e64 v71, v12, v71, s[10:11]
	v_cmp_gt_u32_e64 s[10:11], v3, 41
	v_cndmask_b32_e64 v72, v12, v72, vcc
	v_cmp_gt_u32_e64 vcc, v3, 42
	v_cndmask_b32_e64 v73, v12, v73, s[6:7]
	v_cmp_gt_u32_e64 s[6:7], v3, 43
	v_cndmask_b32_e64 v74, v12, v74, s[10:11]
	v_cmp_gt_u32_e64 s[10:11], v3, 44
	v_cndmask_b32_e64 v75, v12, v75, vcc
	v_cmp_gt_u32_e64 vcc, v3, 45
	v_cndmask_b32_e64 v76, v12, v76, s[6:7]
	v_cmp_gt_u32_e64 s[6:7], v3, 46
	v_cndmask_b32_e64 v77, v12, v77, s[10:11]
	v_cmp_gt_u32_e64 s[10:11], v3, 47
	v_cndmask_b32_e64 v78, v12, v78, vcc
	v_cmp_gt_u32_e64 vcc, v3, 48
	v_cndmask_b32_e64 v79, v12, v79, s[6:7]
	v_cmp_gt_u32_e64 s[6:7], v3, 49
	v_cndmask_b32_e64 v80, v12, v80, s[10:11]
	v_cmp_gt_u32_e64 s[10:11], v3, 50
	v_cndmask_b32_e64 v81, v12, v81, vcc
	v_cmp_gt_u32_e64 vcc, v3, 51
	v_cndmask_b32_e64 v82, v12, v82, s[6:7]
	v_cmp_gt_u32_e64 s[6:7], v3, 52
	v_cndmask_b32_e64 v83, v12, v83, s[10:11]
	v_cmp_gt_u32_e64 s[10:11], v3, 53
	v_cndmask_b32_e64 v84, v12, v84, vcc
	v_cmp_gt_u32_e64 vcc, v3, 54
	v_cndmask_b32_e64 v85, v12, v85, s[6:7]
	v_cmp_gt_u32_e64 s[6:7], v3, 55
	v_cndmask_b32_e64 v86, v12, v86, s[10:11]
	v_cmp_gt_u32_e64 s[10:11], v3, 56
	v_cndmask_b32_e64 v87, v12, v87, vcc
	v_cmp_gt_u32_e64 vcc, v3, 57
	v_cndmask_b32_e64 v88, v12, v88, s[6:7]
	v_cmp_gt_u32_e64 s[6:7], v3, 58
	v_cndmask_b32_e64 v89, v12, v89, s[10:11]
	v_cmp_gt_u32_e64 s[10:11], v3, 59
	v_cndmask_b32_e64 v90, v12, v90, vcc
	v_cmp_gt_u32_e64 vcc, v3, 60
	v_cndmask_b32_e64 v91, v12, v91, s[6:7]
	v_cmp_gt_u32_e64 s[6:7], v3, 61
	v_cndmask_b32_e64 v92, v12, v92, s[10:11]
	v_cmp_gt_u32_e64 s[10:11], v3, 62
	v_cndmask_b32_e64 v93, v12, v93, vcc
	s_nop 1
	v_cndmask_b32_e64 v94, v12, v94, s[6:7]
	v_cndmask_b32_e64 v95, v12, v95, s[10:11]
; DI void nsa_cmp_unit(const Params& p, int u, char* smem) {
;     ...
;         int best = 1; float bv = -1.f;
;         for (int jj = 1; jj < cur; ++jj) {
;           const float v = imp_s[tid * 65 + jj];
;           if (!((mask >> jj) & 1ull) && v > bv) { bv = v; best = jj; }
;         }
.Lsel_round:
	v_mov_b32_e32 v8, 1
	v_mov_b32_e32 v9, -1.0
	v_cmp_gt_f32_e64 s[10:11], v34, v9
	s_nop 0
	s_nop 0
	v_cndmask_b32_e64 v9, v9, v34, s[10:11]
	v_cmp_gt_f32_e64 s[6:7], v35, v9
	v_cndmask_b32_e64 v8, v8, 1, s[10:11]
	s_nop 0
	v_cndmask_b32_e64 v9, v9, v35, s[6:7]
	v_cmp_gt_f32_e64 s[10:11], v36, v9
	v_cndmask_b32_e64 v8, v8, 2, s[6:7]
	s_nop 0
	v_cndmask_b32_e64 v9, v9, v36, s[10:11]
	v_cmp_gt_f32_e64 s[6:7], v37, v9
	v_cndmask_b32_e64 v8, v8, 3, s[10:11]
	s_nop 0
	v_cndmask_b32_e64 v9, v9, v37, s[6:7]
	v_cmp_gt_f32_e64 s[10:11], v38, v9
	v_cndmask_b32_e64 v8, v8, 4, s[6:7]
	s_nop 0
	v_cndmask_b32_e64 v9, v9, v38, s[10:11]
	v_cmp_gt_f32_e64 s[6:7], v39, v9
	v_cndmask_b32_e64 v8, v8, 5, s[10:11]
	s_nop 0
	v_cndmask_b32_e64 v9, v9, v39, s[6:7]
	v_cmp_gt_f32_e64 s[10:11], v40, v9
	v_cndmask_b32_e64 v8, v8, 6, s[6:7]
	s_nop 0
	v_cndmask_b32_e64 v9, v9, v40, s[10:11]
	v_cmp_gt_f32_e64 s[6:7], v41, v9
	v_cndmask_b32_e64 v8, v8, 7, s[10:11]
	s_nop 0
	v_cndmask_b32_e64 v9, v9, v41, s[6:7]
	v_cmp_gt_f32_e64 s[10:11], v42, v9
	v_cndmask_b32_e64 v8, v8, 8, s[6:7]
	s_nop 0
	v_cndmask_b32_e64 v9, v9, v42, s[10:11]
	v_cmp_gt_f32_e64 s[6:7], v43, v9
	v_cndmask_b32_e64 v8, v8, 9, s[10:11]
	s_nop 0
	v_cndmask_b32_e64 v9, v9, v43, s[6:7]
	v_cmp_gt_f32_e64 s[10:11], v44, v9
	v_cndmask_b32_e64 v8, v8, 10, s[6:7]
	s_nop 0
	v_cndmask_b32_e64 v9, v9, v44, s[10:11]
	v_cmp_gt_f32_e64 s[6:7], v45, v9
	v_cndmask_b32_e64 v8, v8, 11, s[10:11]
	s_nop 0
	v_cndmask_b32_e64 v9, v9, v45, s[6:7]
	v_cmp_gt_f32_e64 s[10:11], v46, v9
	v_cndmask_b32_e64 v8, v8, 12, s[6:7]
	s_nop 0
	v_cndmask_b32_e64 v9, v9, v46, s[10:11]
	v_cmp_gt_f32_e64 s[6:7], v47, v9
	v_cndmask_b32_e64 v8, v8, 13, s[10:11]
	s_nop 0
	v_cndmask_b32_e64 v9, v9, v47, s[6:7]
	v_cmp_gt_f32_e64 s[10:11], v48, v9
	v_cndmask_b32_e64 v8, v8, 14, s[6:7]
	s_nop 0
	v_cndmask_b32_e64 v9, v9, v48, s[10:11]
	v_cmp_gt_f32_e64 s[6:7], v49, v9
	v_cndmask_b32_e64 v8, v8, 15, s[10:11]
	s_nop 0
	v_cndmask_b32_e64 v9, v9, v49, s[6:7]
	v_cmp_gt_f32_e64 s[10:11], v50, v9
	v_cndmask_b32_e64 v8, v8, 16, s[6:7]
	s_nop 0
	v_cndmask_b32_e64 v9, v9, v50, s[10:11]
	v_cmp_gt_f32_e64 s[6:7], v51, v9
	v_cndmask_b32_e64 v8, v8, 17, s[10:11]
	s_nop 0
	v_cndmask_b32_e64 v9, v9, v51, s[6:7]
	v_cmp_gt_f32_e64 s[10:11], v52, v9
	v_cndmask_b32_e64 v8, v8, 18, s[6:7]
	s_nop 0
	v_cndmask_b32_e64 v9, v9, v52, s[10:11]
	v_cmp_gt_f32_e64 s[6:7], v53, v9
	v_cndmask_b32_e64 v8, v8, 19, s[10:11]
	s_nop 0
	v_cndmask_b32_e64 v9, v9, v53, s[6:7]
	v_cmp_gt_f32_e64 s[10:11], v54, v9
	v_cndmask_b32_e64 v8, v8, 20, s[6:7]
	s_nop 0
	v_cndmask_b32_e64 v9, v9, v54, s[10:11]
	v_cmp_gt_f32_e64 s[6:7], v55, v9
	v_cndmask_b32_e64 v8, v8, 21, s[10:11]
	s_nop 0
	v_cndmask_b32_e64 v9, v9, v55, s[6:7]
	v_cmp_gt_f32_e64 s[10:11], v56, v9
	v_cndmask_b32_e64 v8, v8, 22, s[6:7]
	s_nop 0
	v_cndmask_b32_e64 v9, v9, v56, s[10:11]
	v_cmp_gt_f32_e64 s[6:7], v57, v9
	v_cndmask_b32_e64 v8, v8, 23, s[10:11]
	s_nop 0
	v_cndmask_b32_e64 v9, v9, v57, s[6:7]
	v_cmp_gt_f32_e64 s[10:11], v58, v9
	v_cndmask_b32_e64 v8, v8, 24, s[6:7]
	s_nop 0
	v_cndmask_b32_e64 v9, v9, v58, s[10:11]
	v_cmp_gt_f32_e64 s[6:7], v59, v9
	v_cndmask_b32_e64 v8, v8, 25, s[10:11]
	s_nop 0
	v_cndmask_b32_e64 v9, v9, v59, s[6:7]
	v_cmp_gt_f32_e64 s[10:11], v60, v9
	v_cndmask_b32_e64 v8, v8, 26, s[6:7]
	s_nop 0
	v_cndmask_b32_e64 v9, v9, v60, s[10:11]
	v_cmp_gt_f32_e64 s[6:7], v61, v9
	v_cndmask_b32_e64 v8, v8, 27, s[10:11]
	s_nop 0
	v_cndmask_b32_e64 v9, v9, v61, s[6:7]
	v_cmp_gt_f32_e64 s[10:11], v62, v9
	v_cndmask_b32_e64 v8, v8, 28, s[6:7]
	s_nop 0
	v_cndmask_b32_e64 v9, v9, v62, s[10:11]
	v_cmp_gt_f32_e64 s[6:7], v63, v9
	v_cndmask_b32_e64 v8, v8, 29, s[10:11]
	s_nop 0
	v_cndmask_b32_e64 v9, v9, v63, s[6:7]
	v_cmp_gt_f32_e64 s[10:11], v64, v9
	v_cndmask_b32_e64 v8, v8, 30, s[6:7]
	s_nop 0
	v_cndmask_b32_e64 v9, v9, v64, s[10:11]
	v_cmp_gt_f32_e64 s[6:7], v65, v9
	v_cndmask_b32_e64 v8, v8, 31, s[10:11]
	s_nop 0
	v_cndmask_b32_e64 v9, v9, v65, s[6:7]
	v_cmp_gt_f32_e64 s[10:11], v66, v9
	v_cndmask_b32_e64 v8, v8, 32, s[6:7]
	s_nop 0
	v_cndmask_b32_e64 v9, v9, v66, s[10:11]
	v_cmp_gt_f32_e64 s[6:7], v67, v9
	v_cndmask_b32_e64 v8, v8, 33, s[10:11]
	s_nop 0
	v_cndmask_b32_e64 v9, v9, v67, s[6:7]
	v_cmp_gt_f32_e64 s[10:11], v68, v9
	v_cndmask_b32_e64 v8, v8, 34, s[6:7]
	s_nop 0
	v_cndmask_b32_e64 v9, v9, v68, s[10:11]
	v_cmp_gt_f32_e64 s[6:7], v69, v9
	v_cndmask_b32_e64 v8, v8, 35, s[10:11]
	s_nop 0
	v_cndmask_b32_e64 v9, v9, v69, s[6:7]
	v_cmp_gt_f32_e64 s[10:11], v70, v9
	v_cndmask_b32_e64 v8, v8, 36, s[6:7]
	s_nop 0
	v_cndmask_b32_e64 v9, v9, v70, s[10:11]
	v_cmp_gt_f32_e64 s[6:7], v71, v9
	v_cndmask_b32_e64 v8, v8, 37, s[10:11]
	s_nop 0
	v_cndmask_b32_e64 v9, v9, v71, s[6:7]
	v_cmp_gt_f32_e64 s[10:11], v72, v9
	v_cndmask_b32_e64 v8, v8, 38, s[6:7]
	s_nop 0
	v_cndmask_b32_e64 v9, v9, v72, s[10:11]
	v_cmp_gt_f32_e64 s[6:7], v73, v9
	v_cndmask_b32_e64 v8, v8, 39, s[10:11]
	s_nop 0
	v_cndmask_b32_e64 v9, v9, v73, s[6:7]
	v_cmp_gt_f32_e64 s[10:11], v74, v9
	v_cndmask_b32_e64 v8, v8, 40, s[6:7]
	s_nop 0
	v_cndmask_b32_e64 v9, v9, v74, s[10:11]
	v_cmp_gt_f32_e64 s[6:7], v75, v9
	v_cndmask_b32_e64 v8, v8, 41, s[10:11]
	s_nop 0
	v_cndmask_b32_e64 v9, v9, v75, s[6:7]
	v_cmp_gt_f32_e64 s[10:11], v76, v9
	v_cndmask_b32_e64 v8, v8, 42, s[6:7]
	s_nop 0
	v_cndmask_b32_e64 v9, v9, v76, s[10:11]
	v_cmp_gt_f32_e64 s[6:7], v77, v9
	v_cndmask_b32_e64 v8, v8, 43, s[10:11]
	s_nop 0
	v_cndmask_b32_e64 v9, v9, v77, s[6:7]
	v_cmp_gt_f32_e64 s[10:11], v78, v9
	v_cndmask_b32_e64 v8, v8, 44, s[6:7]
	s_nop 0
	v_cndmask_b32_e64 v9, v9, v78, s[10:11]
	v_cmp_gt_f32_e64 s[6:7], v79, v9
	v_cndmask_b32_e64 v8, v8, 45, s[10:11]
	s_nop 0
; DI void nsa_cmp_unit(const Params& p, int u, char* smem) {
;     ...
;       for (int k = 0; k < need; ++k) {
;         int best = 1; float bv = -1.f;
;         for (int jj = 1; jj < cur; ++jj) {
;           const float v = imp_s[tid * 65 + jj];
;           if (!((mask >> jj) & 1ull) && v > bv) { bv = v; best = jj; }
;         }
;         mask |= 1ull << best;
;       }
;     }
;     p.selmask[(size_t)(b * 2 + g) * SEQ + t] = mask;
	v_cndmask_b32_e64 v9, v9, v79, s[6:7]
	v_cmp_gt_f32_e64 s[10:11], v80, v9
	v_cndmask_b32_e64 v8, v8, 46, s[6:7]
	s_nop 0
	v_cndmask_b32_e64 v9, v9, v80, s[10:11]
	v_cmp_gt_f32_e64 s[6:7], v81, v9
	v_cndmask_b32_e64 v8, v8, 47, s[10:11]
	s_nop 0
	v_cndmask_b32_e64 v9, v9, v81, s[6:7]
	v_cmp_gt_f32_e64 s[10:11], v82, v9
	v_cndmask_b32_e64 v8, v8, 48, s[6:7]
	s_nop 0
	v_cndmask_b32_e64 v9, v9, v82, s[10:11]
	v_cmp_gt_f32_e64 s[6:7], v83, v9
	v_cndmask_b32_e64 v8, v8, 49, s[10:11]
	s_nop 0
	v_cndmask_b32_e64 v9, v9, v83, s[6:7]
	v_cmp_gt_f32_e64 s[10:11], v84, v9
	v_cndmask_b32_e64 v8, v8, 50, s[6:7]
	s_nop 0
	v_cndmask_b32_e64 v9, v9, v84, s[10:11]
	v_cmp_gt_f32_e64 s[6:7], v85, v9
	v_cndmask_b32_e64 v8, v8, 51, s[10:11]
	s_nop 0
	v_cndmask_b32_e64 v9, v9, v85, s[6:7]
	v_cmp_gt_f32_e64 s[10:11], v86, v9
	v_cndmask_b32_e64 v8, v8, 52, s[6:7]
	s_nop 0
	v_cndmask_b32_e64 v9, v9, v86, s[10:11]
	v_cmp_gt_f32_e64 s[6:7], v87, v9
	v_cndmask_b32_e64 v8, v8, 53, s[10:11]
	s_nop 0
	v_cndmask_b32_e64 v9, v9, v87, s[6:7]
	v_cmp_gt_f32_e64 s[10:11], v88, v9
	v_cndmask_b32_e64 v8, v8, 54, s[6:7]
	s_nop 0
	v_cndmask_b32_e64 v9, v9, v88, s[10:11]
	v_cmp_gt_f32_e64 s[6:7], v89, v9
	v_cndmask_b32_e64 v8, v8, 55, s[10:11]
	s_nop 0
	v_cndmask_b32_e64 v9, v9, v89, s[6:7]
	v_cmp_gt_f32_e64 s[10:11], v90, v9
	v_cndmask_b32_e64 v8, v8, 56, s[6:7]
	s_nop 0
	v_cndmask_b32_e64 v9, v9, v90, s[10:11]
	v_cmp_gt_f32_e64 s[6:7], v91, v9
	v_cndmask_b32_e64 v8, v8, 57, s[10:11]
	s_nop 0
	v_cndmask_b32_e64 v9, v9, v91, s[6:7]
	v_cmp_gt_f32_e64 s[10:11], v92, v9
	v_cndmask_b32_e64 v8, v8, 58, s[6:7]
	s_nop 0
	v_cndmask_b32_e64 v9, v9, v92, s[10:11]
	v_cmp_gt_f32_e64 s[6:7], v93, v9
	v_cndmask_b32_e64 v8, v8, 59, s[10:11]
	s_nop 0
	v_cndmask_b32_e64 v9, v9, v93, s[6:7]
	v_cmp_gt_f32_e64 s[10:11], v94, v9
	v_cndmask_b32_e64 v8, v8, 60, s[6:7]
	s_nop 0
	v_cndmask_b32_e64 v9, v9, v94, s[10:11]
	v_cmp_gt_f32_e64 s[6:7], v95, v9
	v_cndmask_b32_e64 v8, v8, 61, s[10:11]
	s_nop 0
	v_cndmask_b32_e64 v9, v9, v95, s[6:7]
	v_cndmask_b32_e64 v8, v8, 62, s[6:7]
	v_cmp_eq_u32_e64 s[6:7], v8, 1
	v_cmp_eq_u32_e64 s[10:11], v8, 2
	v_cmp_eq_u32_e64 vcc, v8, 3
	v_cndmask_b32_e64 v34, v34, v12, s[6:7]
	v_cmp_eq_u32_e64 s[6:7], v8, 4
	v_cndmask_b32_e64 v35, v35, v12, s[10:11]
	v_cmp_eq_u32_e64 s[10:11], v8, 5
	v_cndmask_b32_e64 v36, v36, v12, vcc
	v_cmp_eq_u32_e64 vcc, v8, 6
	v_cndmask_b32_e64 v37, v37, v12, s[6:7]
	v_cmp_eq_u32_e64 s[6:7], v8, 7
	v_cndmask_b32_e64 v38, v38, v12, s[10:11]
	v_cmp_eq_u32_e64 s[10:11], v8, 8
	v_cndmask_b32_e64 v39, v39, v12, vcc
	v_cmp_eq_u32_e64 vcc, v8, 9
	v_cndmask_b32_e64 v40, v40, v12, s[6:7]
	v_cmp_eq_u32_e64 s[6:7], v8, 10
	v_cndmask_b32_e64 v41, v41, v12, s[10:11]
	v_cmp_eq_u32_e64 s[10:11], v8, 11
	v_cndmask_b32_e64 v42, v42, v12, vcc
	v_cmp_eq_u32_e64 vcc, v8, 12
	v_cndmask_b32_e64 v43, v43, v12, s[6:7]
	v_cmp_eq_u32_e64 s[6:7], v8, 13
	v_cndmask_b32_e64 v44, v44, v12, s[10:11]
	v_cmp_eq_u32_e64 s[10:11], v8, 14
	v_cndmask_b32_e64 v45, v45, v12, vcc
	v_cmp_eq_u32_e64 vcc, v8, 15
	v_cndmask_b32_e64 v46, v46, v12, s[6:7]
	v_cmp_eq_u32_e64 s[6:7], v8, 16
	v_cndmask_b32_e64 v47, v47, v12, s[10:11]
	v_cmp_eq_u32_e64 s[10:11], v8, 17
	v_cndmask_b32_e64 v48, v48, v12, vcc
	v_cmp_eq_u32_e64 vcc, v8, 18
	v_cndmask_b32_e64 v49, v49, v12, s[6:7]
	v_cmp_eq_u32_e64 s[6:7], v8, 19
	v_cndmask_b32_e64 v50, v50, v12, s[10:11]
	v_cmp_eq_u32_e64 s[10:11], v8, 20
	v_cndmask_b32_e64 v51, v51, v12, vcc
	v_cmp_eq_u32_e64 vcc, v8, 21
	v_cndmask_b32_e64 v52, v52, v12, s[6:7]
	v_cmp_eq_u32_e64 s[6:7], v8, 22
	v_cndmask_b32_e64 v53, v53, v12, s[10:11]
	v_cmp_eq_u32_e64 s[10:11], v8, 23
	v_cndmask_b32_e64 v54, v54, v12, vcc
	v_cmp_eq_u32_e64 vcc, v8, 24
	v_cndmask_b32_e64 v55, v55, v12, s[6:7]
	v_cmp_eq_u32_e64 s[6:7], v8, 25
	v_cndmask_b32_e64 v56, v56, v12, s[10:11]
	v_cmp_eq_u32_e64 s[10:11], v8, 26
	v_cndmask_b32_e64 v57, v57, v12, vcc
	v_cmp_eq_u32_e64 vcc, v8, 27
	v_cndmask_b32_e64 v58, v58, v12, s[6:7]
	v_cmp_eq_u32_e64 s[6:7], v8, 28
	v_cndmask_b32_e64 v59, v59, v12, s[10:11]
	v_cmp_eq_u32_e64 s[10:11], v8, 29
	v_cndmask_b32_e64 v60, v60, v12, vcc
	v_cmp_eq_u32_e64 vcc, v8, 30
	v_cndmask_b32_e64 v61, v61, v12, s[6:7]
	v_cmp_eq_u32_e64 s[6:7], v8, 31
	v_cndmask_b32_e64 v62, v62, v12, s[10:11]
	v_cmp_eq_u32_e64 s[10:11], v8, 32
	v_cndmask_b32_e64 v63, v63, v12, vcc
	v_cmp_eq_u32_e64 vcc, v8, 33
	v_cndmask_b32_e64 v64, v64, v12, s[6:7]
	v_cmp_eq_u32_e64 s[6:7], v8, 34
	v_cndmask_b32_e64 v65, v65, v12, s[10:11]
	v_cmp_eq_u32_e64 s[10:11], v8, 35
	v_cndmask_b32_e64 v66, v66, v12, vcc
	v_cmp_eq_u32_e64 vcc, v8, 36
	v_cndmask_b32_e64 v67, v67, v12, s[6:7]
	v_cmp_eq_u32_e64 s[6:7], v8, 37
	v_cndmask_b32_e64 v68, v68, v12, s[10:11]
	v_cmp_eq_u32_e64 s[10:11], v8, 38
	v_cndmask_b32_e64 v69, v69, v12, vcc
	v_cmp_eq_u32_e64 vcc, v8, 39
	v_cndmask_b32_e64 v70, v70, v12, s[6:7]
	v_cmp_eq_u32_e64 s[6:7], v8, 40
	v_cndmask_b32_e64 v71, v71, v12, s[10:11]
	v_cmp_eq_u32_e64 s[10:11], v8, 41
	v_cndmask_b32_e64 v72, v72, v12, vcc
	v_cmp_eq_u32_e64 vcc, v8, 42
	v_cndmask_b32_e64 v73, v73, v12, s[6:7]
	v_cmp_eq_u32_e64 s[6:7], v8, 43
	v_cndmask_b32_e64 v74, v74, v12, s[10:11]
	v_cmp_eq_u32_e64 s[10:11], v8, 44
	v_cndmask_b32_e64 v75, v75, v12, vcc
	v_cmp_eq_u32_e64 vcc, v8, 45
	v_cndmask_b32_e64 v76, v76, v12, s[6:7]
	v_cmp_eq_u32_e64 s[6:7], v8, 46
	v_cndmask_b32_e64 v77, v77, v12, s[10:11]
	v_cmp_eq_u32_e64 s[10:11], v8, 47
	v_cndmask_b32_e64 v78, v78, v12, vcc
	v_cmp_eq_u32_e64 vcc, v8, 48
	v_cndmask_b32_e64 v79, v79, v12, s[6:7]
	v_cmp_eq_u32_e64 s[6:7], v8, 49
	v_cndmask_b32_e64 v80, v80, v12, s[10:11]
	v_cmp_eq_u32_e64 s[10:11], v8, 50
	v_cndmask_b32_e64 v81, v81, v12, vcc
	v_cmp_eq_u32_e64 vcc, v8, 51
	v_cndmask_b32_e64 v82, v82, v12, s[6:7]
	v_cmp_eq_u32_e64 s[6:7], v8, 52
	v_cndmask_b32_e64 v83, v83, v12, s[10:11]
	v_cmp_eq_u32_e64 s[10:11], v8, 53
	v_cndmask_b32_e64 v84, v84, v12, vcc
	v_cmp_eq_u32_e64 vcc, v8, 54
	v_cndmask_b32_e64 v85, v85, v12, s[6:7]
	v_cmp_eq_u32_e64 s[6:7], v8, 55
	v_cndmask_b32_e64 v86, v86, v12, s[10:11]
	v_cmp_eq_u32_e64 s[10:11], v8, 56
	v_cndmask_b32_e64 v87, v87, v12, vcc
	v_cmp_eq_u32_e64 vcc, v8, 57
	v_cndmask_b32_e64 v88, v88, v12, s[6:7]
	v_cmp_eq_u32_e64 s[6:7], v8, 58
	v_cndmask_b32_e64 v89, v89, v12, s[10:11]
	v_cmp_eq_u32_e64 s[10:11], v8, 59
	v_cndmask_b32_e64 v90, v90, v12, vcc
	v_cmp_eq_u32_e64 vcc, v8, 60
	v_cndmask_b32_e64 v91, v91, v12, s[6:7]
	v_cmp_eq_u32_e64 s[6:7], v8, 61
	v_cndmask_b32_e64 v92, v92, v12, s[10:11]
	v_cmp_eq_u32_e64 s[10:11], v8, 62
	v_cndmask_b32_e64 v93, v93, v12, vcc
	s_nop 1
	v_cndmask_b32_e64 v94, v94, v12, s[6:7]
	v_cndmask_b32_e64 v95, v95, v12, s[10:11]
	v_lshlrev_b64 v[10:11], v8, 1
	v_or_b32_e32 v4, v10, v4
	v_or_b32_e32 v5, v11, v5
	s_add_i32 s100, s100, -1
	s_cmp_lg_u32 s100, 0
	s_cbranch_scc1 .Lsel_round
	s_branch .LBB0_428
.Lsel_small:
	s_mov_b32 s28, 0
	s_mov_b64 s[10:11], 0
